# P1 rotary epilogue: vmcnt(0) after the 16 cos/sin loads replaced by a counted ladder (each row group waits only for its own two loads)
# speedup vs baseline: 1.0018x; 1.0018x over previous
; __device__ __forceinline__ unsigned cvt_pk_bf16(float lo, float hi) { unsigned r; asm volatile("v_cvt_pk_bf16_f32 %0, %1, %2" : "=v"(r) : "v"(lo), "v"(hi)); return r; }
;     __device__ __forceinline__ void operator()(const f32x4 (&acc)[2][2][4][2], const Unit& u, int wr, int wc, int fr_, int fq_) const {
;     ...
;             for (int bj = 0; bj < 2; ++bj) {
;                 f32x4 v0 = acc[ai][bj][m][0], v1 = acc[ai][bj][m][1];
;                 if (rotl) {
;                     f32x4 w0, w1;
;                     w0[0] = v0[0] * cs0[0] - v0[1] * cs0[1]; w0[1] = v0[1] * cs0[0] + v0[0] * cs0[1];
;                     w0[2] = v0[2] * cs1[0] - v0[3] * cs1[1]; w0[3] = v0[3] * cs1[0] + v0[2] * cs1[1];
;                     w1[0] = v1[0] * cs2[0] - v1[1] * cs2[1]; w1[1] = v1[1] * cs2[0] + v1[0] * cs2[1];
;                     w1[2] = v1[2] * cs3[0] - v1[3] * cs3[1]; w1[3] = v1[3] * cs3[0] + v1[2] * cs3[1];
;                     v0 = w0; v1 = w1;
;                 }
;                 u32x4 w; w.x = cvt_pk_bf16(v0[0], v0[1]); w.y = cvt_pk_bf16(v0[2], v0[3]); w.z = cvt_pk_bf16(v1[0], v1[1]); w.w = cvt_pk_bf16(v1[2], v1[3]);
;                 *(u32x4*)(rowp + bj * hstep) = w;
.LBB0_191:
	s_and_saveexec_b64 s[44:45], s[38:39]
	s_cbranch_execz .LBB0_193
	s_waitcnt vmcnt(14)
	v_pk_mul_f32 v[230:231], v[166:167], v[190:191] op_sel:[1,1] op_sel_hi:[0,1]
	v_pk_mul_f32 v[228:229], v[166:167], v[190:191]
	v_pk_fma_f32 v[166:167], v[166:167], v[190:191], v[230:231] op_sel_hi:[1,0,1]
	v_pk_mul_f32 v[236:237], v[162:163], v[186:187] op_sel:[1,1] op_sel_hi:[0,1]
	v_mul_f32_e32 v166, v169, v193
	v_pk_fma_f32 v[232:233], v[168:169], v[192:193], v[166:167] op_sel_hi:[1,1,0] neg_lo:[0,0,1] neg_hi:[0,0,1]
	v_mul_f32_e32 v166, v168, v193
	v_pk_fma_f32 v[234:235], v[168:169], v[192:193], v[166:167] op_sel:[1,0,0] op_sel_hi:[0,1,0]
	v_pk_mul_f32 v[168:169], v[162:163], v[186:187]
	v_pk_fma_f32 v[162:163], v[162:163], v[186:187], v[236:237] op_sel_hi:[1,0,1]
	v_sub_f32_e32 v166, v228, v230
	v_mul_f32_e32 v162, v165, v189
	v_pk_fma_f32 v[238:239], v[164:165], v[188:189], v[162:163] op_sel_hi:[1,1,0] neg_lo:[0,0,1] neg_hi:[0,0,1]
	v_mul_f32_e32 v162, v164, v189
	v_pk_fma_f32 v[240:241], v[164:165], v[188:189], v[162:163] op_sel:[1,0,0] op_sel_hi:[0,1,0]
	v_sub_f32_e32 v162, v168, v236
	v_mov_b32_e32 v168, v232
	v_mov_b32_e32 v169, v234
	v_mov_b32_e32 v164, v238
	v_mov_b32_e32 v165, v240
.LBB0_193:
	s_or_b64 exec, exec, s[44:45]
	v_cvt_pk_bf16_f32 v166, v166, v167
	v_cvt_pk_bf16_f32 v167, v168, v169
	v_cvt_pk_bf16_f32 v168, v162, v163
	v_cvt_pk_bf16_f32 v169, v164, v165
	global_store_dwordx4 v[216:217], v[166:169], off
	s_and_saveexec_b64 s[44:45], s[38:39]
	s_cbranch_execz .LBB0_195
	s_waitcnt vmcnt(14)
	s_nop 1
	v_pk_mul_f32 v[164:165], v[158:159], v[190:191] op_sel:[1,1] op_sel_hi:[0,1]
	v_pk_mul_f32 v[162:163], v[158:159], v[190:191]
	v_pk_fma_f32 v[158:159], v[158:159], v[190:191], v[164:165] op_sel_hi:[1,0,1]
	v_pk_mul_f32 v[190:191], v[154:155], v[186:187] op_sel:[1,1] op_sel_hi:[0,1]
	v_mul_f32_e32 v158, v161, v193
	v_pk_fma_f32 v[166:167], v[160:161], v[192:193], v[158:159] op_sel_hi:[1,1,0] neg_lo:[0,0,1] neg_hi:[0,0,1]
	v_mul_f32_e32 v158, v160, v193
	v_pk_fma_f32 v[168:169], v[160:161], v[192:193], v[158:159] op_sel:[1,0,0] op_sel_hi:[0,1,0]
	v_pk_mul_f32 v[160:161], v[154:155], v[186:187]
	v_pk_fma_f32 v[154:155], v[154:155], v[186:187], v[190:191] op_sel_hi:[1,0,1]
	v_sub_f32_e32 v158, v162, v164
	v_mul_f32_e32 v154, v157, v189
	v_pk_fma_f32 v[186:187], v[156:157], v[188:189], v[154:155] op_sel_hi:[1,1,0] neg_lo:[0,0,1] neg_hi:[0,0,1]
	v_mul_f32_e32 v154, v156, v189
	v_pk_fma_f32 v[188:189], v[156:157], v[188:189], v[154:155] op_sel:[1,0,0] op_sel_hi:[0,1,0]
	v_sub_f32_e32 v154, v160, v190
	v_mov_b32_e32 v160, v166
	v_mov_b32_e32 v161, v168
	v_mov_b32_e32 v156, v186
	v_mov_b32_e32 v157, v188

; __device__ __forceinline__ unsigned cvt_pk_bf16(float lo, float hi) { unsigned r; asm volatile("v_cvt_pk_bf16_f32 %0, %1, %2" : "=v"(r) : "v"(lo), "v"(hi)); return r; }
;     __device__ __forceinline__ void operator()(const f32x4 (&acc)[2][2][4][2], const Unit& u, int wr, int wc, int fr_, int fq_) const {
;     ...
;             for (int bj = 0; bj < 2; ++bj) {
;                 f32x4 v0 = acc[ai][bj][m][0], v1 = acc[ai][bj][m][1];
;                 if (rotl) {
;                     f32x4 w0, w1;
;                     w0[0] = v0[0] * cs0[0] - v0[1] * cs0[1]; w0[1] = v0[1] * cs0[0] + v0[0] * cs0[1];
;                     w0[2] = v0[2] * cs1[0] - v0[3] * cs1[1]; w0[3] = v0[3] * cs1[0] + v0[2] * cs1[1];
;                     w1[0] = v1[0] * cs2[0] - v1[1] * cs2[1]; w1[1] = v1[1] * cs2[0] + v1[0] * cs2[1];
;                     w1[2] = v1[2] * cs3[0] - v1[3] * cs3[1]; w1[3] = v1[3] * cs3[0] + v1[2] * cs3[1];
;                     v0 = w0; v1 = w1;
;                 }
;                 u32x4 w; w.x = cvt_pk_bf16(v0[0], v0[1]); w.y = cvt_pk_bf16(v0[2], v0[3]); w.z = cvt_pk_bf16(v1[0], v1[1]); w.w = cvt_pk_bf16(v1[2], v1[3]);
;                 *(u32x4*)(rowp + bj * hstep) = w;
.LBB0_200:
	s_waitcnt vmcnt(12)
	s_nop 1
	v_pk_mul_f32 v[158:159], v[142:143], v[182:183] op_sel:[1,1] op_sel_hi:[0,1]
	v_pk_mul_f32 v[156:157], v[142:143], v[182:183]
	v_pk_fma_f32 v[142:143], v[142:143], v[182:183], v[158:159] op_sel_hi:[1,0,1]
	v_pk_mul_f32 v[164:165], v[138:139], v[178:179] op_sel:[1,1] op_sel_hi:[0,1]
	v_mul_f32_e32 v142, v145, v185
	v_pk_fma_f32 v[160:161], v[144:145], v[184:185], v[142:143] op_sel_hi:[1,1,0] neg_lo:[0,0,1] neg_hi:[0,0,1]
	v_mul_f32_e32 v142, v144, v185
	v_pk_fma_f32 v[162:163], v[144:145], v[184:185], v[142:143] op_sel:[1,0,0] op_sel_hi:[0,1,0]
	v_pk_mul_f32 v[144:145], v[138:139], v[178:179]
	v_pk_fma_f32 v[138:139], v[138:139], v[178:179], v[164:165] op_sel_hi:[1,0,1]
	v_sub_f32_e32 v142, v156, v158
	v_mul_f32_e32 v138, v141, v181
	v_pk_fma_f32 v[166:167], v[140:141], v[180:181], v[138:139] op_sel_hi:[1,1,0] neg_lo:[0,0,1] neg_hi:[0,0,1]
	v_mul_f32_e32 v138, v140, v181
	v_pk_fma_f32 v[168:169], v[140:141], v[180:181], v[138:139] op_sel:[1,0,0] op_sel_hi:[0,1,0]
	v_sub_f32_e32 v138, v144, v164
	v_mov_b32_e32 v144, v160
	v_mov_b32_e32 v145, v162
	v_mov_b32_e32 v140, v166
	v_mov_b32_e32 v141, v168
.LBB0_201:
	s_or_b64 exec, exec, s[44:45]
	v_cvt_pk_bf16_f32 v142, v142, v143
	v_cvt_pk_bf16_f32 v143, v144, v145
	v_cvt_pk_bf16_f32 v144, v138, v139
	v_cvt_pk_bf16_f32 v145, v140, v141
	global_store_dwordx4 v[154:155], v[142:145], off
	s_and_saveexec_b64 s[44:45], s[38:39]
	s_cbranch_execz .LBB0_203
	s_waitcnt vmcnt(12)
	s_nop 1
	v_pk_mul_f32 v[140:141], v[134:135], v[182:183] op_sel:[1,1] op_sel_hi:[0,1]
	v_pk_mul_f32 v[138:139], v[134:135], v[182:183]
	v_pk_fma_f32 v[134:135], v[134:135], v[182:183], v[140:141] op_sel_hi:[1,0,1]
	v_pk_mul_f32 v[156:157], v[130:131], v[178:179] op_sel:[1,1] op_sel_hi:[0,1]
	v_mul_f32_e32 v134, v137, v185
	v_pk_fma_f32 v[142:143], v[136:137], v[184:185], v[134:135] op_sel_hi:[1,1,0] neg_lo:[0,0,1] neg_hi:[0,0,1]
	v_mul_f32_e32 v134, v136, v185
	v_pk_fma_f32 v[144:145], v[136:137], v[184:185], v[134:135] op_sel:[1,0,0] op_sel_hi:[0,1,0]
	v_pk_mul_f32 v[136:137], v[130:131], v[178:179]
	v_pk_fma_f32 v[130:131], v[130:131], v[178:179], v[156:157] op_sel_hi:[1,0,1]
	v_sub_f32_e32 v134, v138, v140
	v_mul_f32_e32 v130, v133, v181
	v_pk_fma_f32 v[158:159], v[132:133], v[180:181], v[130:131] op_sel_hi:[1,1,0] neg_lo:[0,0,1] neg_hi:[0,0,1]
	v_mul_f32_e32 v130, v132, v181
	v_pk_fma_f32 v[160:161], v[132:133], v[180:181], v[130:131] op_sel:[1,0,0] op_sel_hi:[0,1,0]
	v_sub_f32_e32 v130, v136, v156
	v_mov_b32_e32 v136, v142
	v_mov_b32_e32 v137, v144
	v_mov_b32_e32 v132, v158
	v_mov_b32_e32 v133, v160

; __device__ __forceinline__ unsigned cvt_pk_bf16(float lo, float hi) { unsigned r; asm volatile("v_cvt_pk_bf16_f32 %0, %1, %2" : "=v"(r) : "v"(lo), "v"(hi)); return r; }
;     __device__ __forceinline__ void operator()(const f32x4 (&acc)[2][2][4][2], const Unit& u, int wr, int wc, int fr_, int fq_) const {
;     ...
;             for (int bj = 0; bj < 2; ++bj) {
;                 f32x4 v0 = acc[ai][bj][m][0], v1 = acc[ai][bj][m][1];
;                 if (rotl) {
;                     f32x4 w0, w1;
;                     w0[0] = v0[0] * cs0[0] - v0[1] * cs0[1]; w0[1] = v0[1] * cs0[0] + v0[0] * cs0[1];
;                     w0[2] = v0[2] * cs1[0] - v0[3] * cs1[1]; w0[3] = v0[3] * cs1[0] + v0[2] * cs1[1];
;                     w1[0] = v1[0] * cs2[0] - v1[1] * cs2[1]; w1[1] = v1[1] * cs2[0] + v1[0] * cs2[1];
;                     w1[2] = v1[2] * cs3[0] - v1[3] * cs3[1]; w1[3] = v1[3] * cs3[0] + v1[2] * cs3[1];
;                     v0 = w0; v1 = w1;
;                 }
;                 u32x4 w; w.x = cvt_pk_bf16(v0[0], v0[1]); w.y = cvt_pk_bf16(v0[2], v0[3]); w.z = cvt_pk_bf16(v1[0], v1[1]); w.w = cvt_pk_bf16(v1[2], v1[3]);
;                 *(u32x4*)(rowp + bj * hstep) = w;
.LBB0_208:
	s_waitcnt vmcnt(10)
	s_nop 1
	v_pk_mul_f32 v[134:135], v[118:119], v[174:175] op_sel:[1,1] op_sel_hi:[0,1]
	v_pk_mul_f32 v[132:133], v[118:119], v[174:175]
	v_pk_fma_f32 v[118:119], v[118:119], v[174:175], v[134:135] op_sel_hi:[1,0,1]
	v_pk_mul_f32 v[140:141], v[114:115], v[170:171] op_sel:[1,1] op_sel_hi:[0,1]
	v_mul_f32_e32 v118, v121, v177
	v_pk_fma_f32 v[136:137], v[120:121], v[176:177], v[118:119] op_sel_hi:[1,1,0] neg_lo:[0,0,1] neg_hi:[0,0,1]
	v_mul_f32_e32 v118, v120, v177
	v_pk_fma_f32 v[138:139], v[120:121], v[176:177], v[118:119] op_sel:[1,0,0] op_sel_hi:[0,1,0]
	v_pk_mul_f32 v[120:121], v[114:115], v[170:171]
	v_pk_fma_f32 v[114:115], v[114:115], v[170:171], v[140:141] op_sel_hi:[1,0,1]
	v_sub_f32_e32 v118, v132, v134
	v_mul_f32_e32 v114, v117, v173
	v_pk_fma_f32 v[142:143], v[116:117], v[172:173], v[114:115] op_sel_hi:[1,1,0] neg_lo:[0,0,1] neg_hi:[0,0,1]
	v_mul_f32_e32 v114, v116, v173
	v_pk_fma_f32 v[144:145], v[116:117], v[172:173], v[114:115] op_sel:[1,0,0] op_sel_hi:[0,1,0]
	v_sub_f32_e32 v114, v120, v140
	v_mov_b32_e32 v120, v136
	v_mov_b32_e32 v121, v138
	v_mov_b32_e32 v116, v142
	v_mov_b32_e32 v117, v144
.LBB0_209:
	s_or_b64 exec, exec, s[44:45]
	v_cvt_pk_bf16_f32 v118, v118, v119
	v_cvt_pk_bf16_f32 v119, v120, v121
	v_cvt_pk_bf16_f32 v120, v114, v115
	v_cvt_pk_bf16_f32 v121, v116, v117
	global_store_dwordx4 v[130:131], v[118:121], off
	s_and_saveexec_b64 s[44:45], s[38:39]
	s_cbranch_execz .LBB0_211
	s_waitcnt vmcnt(10)
	s_nop 1
	v_pk_mul_f32 v[116:117], v[110:111], v[174:175] op_sel:[1,1] op_sel_hi:[0,1]
	v_pk_mul_f32 v[114:115], v[110:111], v[174:175]
	v_pk_fma_f32 v[110:111], v[110:111], v[174:175], v[116:117] op_sel_hi:[1,0,1]
	v_pk_mul_f32 v[132:133], v[98:99], v[170:171] op_sel:[1,1] op_sel_hi:[0,1]
	v_mul_f32_e32 v110, v113, v177
	v_pk_fma_f32 v[118:119], v[112:113], v[176:177], v[110:111] op_sel_hi:[1,1,0] neg_lo:[0,0,1] neg_hi:[0,0,1]
	v_mul_f32_e32 v110, v112, v177
	v_pk_fma_f32 v[120:121], v[112:113], v[176:177], v[110:111] op_sel:[1,0,0] op_sel_hi:[0,1,0]
	v_pk_mul_f32 v[112:113], v[98:99], v[170:171]
	v_pk_fma_f32 v[98:99], v[98:99], v[170:171], v[132:133] op_sel_hi:[1,0,1]
	v_sub_f32_e32 v110, v114, v116
	v_mul_f32_e32 v98, v101, v173
	v_pk_fma_f32 v[134:135], v[100:101], v[172:173], v[98:99] op_sel_hi:[1,1,0] neg_lo:[0,0,1] neg_hi:[0,0,1]
	v_mul_f32_e32 v98, v100, v173
	v_pk_fma_f32 v[136:137], v[100:101], v[172:173], v[98:99] op_sel:[1,0,0] op_sel_hi:[0,1,0]
	v_sub_f32_e32 v98, v112, v132
	v_mov_b32_e32 v112, v118
	v_mov_b32_e32 v113, v120
	v_mov_b32_e32 v100, v134
	v_mov_b32_e32 v101, v136

; __device__ __forceinline__ unsigned cvt_pk_bf16(float lo, float hi) { unsigned r; asm volatile("v_cvt_pk_bf16_f32 %0, %1, %2" : "=v"(r) : "v"(lo), "v"(hi)); return r; }
;     __device__ __forceinline__ void operator()(const f32x4 (&acc)[2][2][4][2], const Unit& u, int wr, int wc, int fr_, int fq_) const {
;     ...
;             for (int bj = 0; bj < 2; ++bj) {
;                 f32x4 v0 = acc[ai][bj][m][0], v1 = acc[ai][bj][m][1];
;                 if (rotl) {
;                     f32x4 w0, w1;
;                     w0[0] = v0[0] * cs0[0] - v0[1] * cs0[1]; w0[1] = v0[1] * cs0[0] + v0[0] * cs0[1];
;                     w0[2] = v0[2] * cs1[0] - v0[3] * cs1[1]; w0[3] = v0[3] * cs1[0] + v0[2] * cs1[1];
;                     w1[0] = v1[0] * cs2[0] - v1[1] * cs2[1]; w1[1] = v1[1] * cs2[0] + v1[0] * cs2[1];
;                     w1[2] = v1[2] * cs3[0] - v1[3] * cs3[1]; w1[3] = v1[3] * cs3[0] + v1[2] * cs3[1];
;                     v0 = w0; v1 = w1;
;                 }
;                 u32x4 w; w.x = cvt_pk_bf16(v0[0], v0[1]); w.y = cvt_pk_bf16(v0[2], v0[3]); w.z = cvt_pk_bf16(v1[0], v1[1]); w.w = cvt_pk_bf16(v1[2], v1[3]);
;                 *(u32x4*)(rowp + bj * hstep) = w;
.LBB0_216:
	s_waitcnt vmcnt(8)
	s_nop 1
	v_pk_mul_f32 v[110:111], v[94:95], v[150:151] op_sel:[1,1] op_sel_hi:[0,1]
	v_pk_mul_f32 v[100:101], v[94:95], v[150:151]
	v_pk_fma_f32 v[94:95], v[94:95], v[150:151], v[110:111] op_sel_hi:[1,0,1]
	v_pk_mul_f32 v[116:117], v[90:91], v[146:147] op_sel:[1,1] op_sel_hi:[0,1]
	v_mul_f32_e32 v94, v97, v153
	v_pk_fma_f32 v[112:113], v[96:97], v[152:153], v[94:95] op_sel_hi:[1,1,0] neg_lo:[0,0,1] neg_hi:[0,0,1]
	v_mul_f32_e32 v94, v96, v153
	v_pk_fma_f32 v[114:115], v[96:97], v[152:153], v[94:95] op_sel:[1,0,0] op_sel_hi:[0,1,0]
	v_pk_mul_f32 v[96:97], v[90:91], v[146:147]
	v_pk_fma_f32 v[90:91], v[90:91], v[146:147], v[116:117] op_sel_hi:[1,0,1]
	v_sub_f32_e32 v94, v100, v110
	v_mul_f32_e32 v90, v93, v149
	v_pk_fma_f32 v[118:119], v[92:93], v[148:149], v[90:91] op_sel_hi:[1,1,0] neg_lo:[0,0,1] neg_hi:[0,0,1]
	v_mul_f32_e32 v90, v92, v149
	v_pk_fma_f32 v[120:121], v[92:93], v[148:149], v[90:91] op_sel:[1,0,0] op_sel_hi:[0,1,0]
	v_sub_f32_e32 v90, v96, v116
	v_mov_b32_e32 v96, v112
	v_mov_b32_e32 v97, v114
	v_mov_b32_e32 v92, v118
	v_mov_b32_e32 v93, v120
.LBB0_217:
	s_or_b64 exec, exec, s[44:45]
	v_cvt_pk_bf16_f32 v94, v94, v95
	v_cvt_pk_bf16_f32 v95, v96, v97
	v_cvt_pk_bf16_f32 v96, v90, v91
	v_cvt_pk_bf16_f32 v97, v92, v93
	global_store_dwordx4 v[98:99], v[94:97], off
	s_and_saveexec_b64 s[44:45], s[38:39]
	s_cbranch_execz .LBB0_219
	s_waitcnt vmcnt(8)
	s_nop 1
	v_pk_mul_f32 v[92:93], v[86:87], v[150:151] op_sel:[1,1] op_sel_hi:[0,1]
	v_pk_mul_f32 v[90:91], v[86:87], v[150:151]
	v_pk_fma_f32 v[86:87], v[86:87], v[150:151], v[92:93] op_sel_hi:[1,0,1]
	v_pk_mul_f32 v[100:101], v[74:75], v[146:147] op_sel:[1,1] op_sel_hi:[0,1]
	v_mul_f32_e32 v86, v89, v153
	v_pk_fma_f32 v[94:95], v[88:89], v[152:153], v[86:87] op_sel_hi:[1,1,0] neg_lo:[0,0,1] neg_hi:[0,0,1]
	v_mul_f32_e32 v86, v88, v153
	v_pk_fma_f32 v[96:97], v[88:89], v[152:153], v[86:87] op_sel:[1,0,0] op_sel_hi:[0,1,0]
	v_pk_mul_f32 v[88:89], v[74:75], v[146:147]
	v_pk_fma_f32 v[74:75], v[74:75], v[146:147], v[100:101] op_sel_hi:[1,0,1]
	v_sub_f32_e32 v86, v90, v92
	v_mul_f32_e32 v74, v77, v149
	v_pk_fma_f32 v[110:111], v[76:77], v[148:149], v[74:75] op_sel_hi:[1,1,0] neg_lo:[0,0,1] neg_hi:[0,0,1]
	v_mul_f32_e32 v74, v76, v149
	v_pk_fma_f32 v[112:113], v[76:77], v[148:149], v[74:75] op_sel:[1,0,0] op_sel_hi:[0,1,0]
	v_sub_f32_e32 v74, v88, v100
	v_mov_b32_e32 v88, v94
	v_mov_b32_e32 v89, v96
	v_mov_b32_e32 v76, v110
	v_mov_b32_e32 v77, v112

; __device__ __forceinline__ unsigned cvt_pk_bf16(float lo, float hi) { unsigned r; asm volatile("v_cvt_pk_bf16_f32 %0, %1, %2" : "=v"(r) : "v"(lo), "v"(hi)); return r; }
;     __device__ __forceinline__ void operator()(const f32x4 (&acc)[2][2][4][2], const Unit& u, int wr, int wc, int fr_, int fq_) const {
;     ...
;             for (int bj = 0; bj < 2; ++bj) {
;                 f32x4 v0 = acc[ai][bj][m][0], v1 = acc[ai][bj][m][1];
;                 if (rotl) {
;                     f32x4 w0, w1;
;                     w0[0] = v0[0] * cs0[0] - v0[1] * cs0[1]; w0[1] = v0[1] * cs0[0] + v0[0] * cs0[1];
;                     w0[2] = v0[2] * cs1[0] - v0[3] * cs1[1]; w0[3] = v0[3] * cs1[0] + v0[2] * cs1[1];
;                     w1[0] = v1[0] * cs2[0] - v1[1] * cs2[1]; w1[1] = v1[1] * cs2[0] + v1[0] * cs2[1];
;                     w1[2] = v1[2] * cs3[0] - v1[3] * cs3[1]; w1[3] = v1[3] * cs3[0] + v1[2] * cs3[1];
;                     v0 = w0; v1 = w1;
;                 }
;                 u32x4 w; w.x = cvt_pk_bf16(v0[0], v0[1]); w.y = cvt_pk_bf16(v0[2], v0[3]); w.z = cvt_pk_bf16(v1[0], v1[1]); w.w = cvt_pk_bf16(v1[2], v1[3]);
;                 *(u32x4*)(rowp + bj * hstep) = w;
.LBB0_224:
	s_waitcnt vmcnt(6)
	s_nop 1
	v_pk_mul_f32 v[86:87], v[70:71], v[126:127] op_sel:[1,1] op_sel_hi:[0,1]
	v_pk_mul_f32 v[76:77], v[70:71], v[126:127]
	v_pk_fma_f32 v[70:71], v[70:71], v[126:127], v[86:87] op_sel_hi:[1,0,1]
	v_pk_mul_f32 v[92:93], v[66:67], v[122:123] op_sel:[1,1] op_sel_hi:[0,1]
	v_mul_f32_e32 v70, v73, v129
	v_pk_fma_f32 v[88:89], v[72:73], v[128:129], v[70:71] op_sel_hi:[1,1,0] neg_lo:[0,0,1] neg_hi:[0,0,1]
	v_mul_f32_e32 v70, v72, v129
	v_pk_fma_f32 v[90:91], v[72:73], v[128:129], v[70:71] op_sel:[1,0,0] op_sel_hi:[0,1,0]
	v_pk_mul_f32 v[72:73], v[66:67], v[122:123]
	v_pk_fma_f32 v[66:67], v[66:67], v[122:123], v[92:93] op_sel_hi:[1,0,1]
	v_sub_f32_e32 v70, v76, v86
	v_mul_f32_e32 v66, v69, v125
	v_pk_fma_f32 v[94:95], v[68:69], v[124:125], v[66:67] op_sel_hi:[1,1,0] neg_lo:[0,0,1] neg_hi:[0,0,1]
	v_mul_f32_e32 v66, v68, v125
	v_pk_fma_f32 v[96:97], v[68:69], v[124:125], v[66:67] op_sel:[1,0,0] op_sel_hi:[0,1,0]
	v_sub_f32_e32 v66, v72, v92
	v_mov_b32_e32 v72, v88
	v_mov_b32_e32 v73, v90
	v_mov_b32_e32 v68, v94
	v_mov_b32_e32 v69, v96
.LBB0_225:
	s_or_b64 exec, exec, s[44:45]
	v_cvt_pk_bf16_f32 v70, v70, v71
	v_cvt_pk_bf16_f32 v71, v72, v73
	v_cvt_pk_bf16_f32 v72, v66, v67
	v_cvt_pk_bf16_f32 v73, v68, v69
	global_store_dwordx4 v[74:75], v[70:73], off
	s_and_saveexec_b64 s[44:45], s[38:39]
	s_cbranch_execz .LBB0_227
	s_waitcnt vmcnt(6)
	s_nop 1
	v_pk_mul_f32 v[68:69], v[54:55], v[126:127] op_sel:[1,1] op_sel_hi:[0,1]
	v_pk_mul_f32 v[66:67], v[54:55], v[126:127]
	v_pk_fma_f32 v[54:55], v[54:55], v[126:127], v[68:69] op_sel_hi:[1,0,1]
	v_pk_mul_f32 v[76:77], v[50:51], v[122:123] op_sel:[1,1] op_sel_hi:[0,1]
	v_mul_f32_e32 v54, v57, v129
	v_pk_fma_f32 v[70:71], v[56:57], v[128:129], v[54:55] op_sel_hi:[1,1,0] neg_lo:[0,0,1] neg_hi:[0,0,1]
	v_mul_f32_e32 v54, v56, v129
	v_pk_fma_f32 v[72:73], v[56:57], v[128:129], v[54:55] op_sel:[1,0,0] op_sel_hi:[0,1,0]
	v_pk_mul_f32 v[56:57], v[50:51], v[122:123]
	v_pk_fma_f32 v[50:51], v[50:51], v[122:123], v[76:77] op_sel_hi:[1,0,1]
	v_sub_f32_e32 v54, v66, v68
	v_mul_f32_e32 v50, v53, v125
	v_pk_fma_f32 v[86:87], v[52:53], v[124:125], v[50:51] op_sel_hi:[1,1,0] neg_lo:[0,0,1] neg_hi:[0,0,1]
	v_mul_f32_e32 v50, v52, v125
	v_pk_fma_f32 v[88:89], v[52:53], v[124:125], v[50:51] op_sel:[1,0,0] op_sel_hi:[0,1,0]
	v_sub_f32_e32 v50, v56, v76
	v_mov_b32_e32 v56, v70
	v_mov_b32_e32 v57, v72
	v_mov_b32_e32 v52, v86
	v_mov_b32_e32 v53, v88

; __device__ __forceinline__ unsigned cvt_pk_bf16(float lo, float hi) { unsigned r; asm volatile("v_cvt_pk_bf16_f32 %0, %1, %2" : "=v"(r) : "v"(lo), "v"(hi)); return r; }
;     __device__ __forceinline__ void operator()(const f32x4 (&acc)[2][2][4][2], const Unit& u, int wr, int wc, int fr_, int fq_) const {
;     ...
;             for (int bj = 0; bj < 2; ++bj) {
;                 f32x4 v0 = acc[ai][bj][m][0], v1 = acc[ai][bj][m][1];
;                 if (rotl) {
;                     f32x4 w0, w1;
;                     w0[0] = v0[0] * cs0[0] - v0[1] * cs0[1]; w0[1] = v0[1] * cs0[0] + v0[0] * cs0[1];
;                     w0[2] = v0[2] * cs1[0] - v0[3] * cs1[1]; w0[3] = v0[3] * cs1[0] + v0[2] * cs1[1];
;                     w1[0] = v1[0] * cs2[0] - v1[1] * cs2[1]; w1[1] = v1[1] * cs2[0] + v1[0] * cs2[1];
;                     w1[2] = v1[2] * cs3[0] - v1[3] * cs3[1]; w1[3] = v1[3] * cs3[0] + v1[2] * cs3[1];
;                     v0 = w0; v1 = w1;
;                 }
;                 u32x4 w; w.x = cvt_pk_bf16(v0[0], v0[1]); w.y = cvt_pk_bf16(v0[2], v0[3]); w.z = cvt_pk_bf16(v1[0], v1[1]); w.w = cvt_pk_bf16(v1[2], v1[3]);
;                 *(u32x4*)(rowp + bj * hstep) = w;
.LBB0_232:
	s_waitcnt vmcnt(3)
	s_nop 1
	v_pk_mul_f32 v[54:55], v[46:47], v[106:107] op_sel:[1,1] op_sel_hi:[0,1]
	v_pk_mul_f32 v[52:53], v[46:47], v[106:107]
	v_pk_fma_f32 v[46:47], v[46:47], v[106:107], v[54:55] op_sel_hi:[1,0,1]
	v_pk_mul_f32 v[68:69], v[42:43], v[102:103] op_sel:[1,1] op_sel_hi:[0,1]
	v_mul_f32_e32 v46, v49, v109
	v_pk_fma_f32 v[56:57], v[48:49], v[108:109], v[46:47] op_sel_hi:[1,1,0] neg_lo:[0,0,1] neg_hi:[0,0,1]
	v_mul_f32_e32 v46, v48, v109
	v_pk_fma_f32 v[66:67], v[48:49], v[108:109], v[46:47] op_sel:[1,0,0] op_sel_hi:[0,1,0]
	v_pk_mul_f32 v[48:49], v[42:43], v[102:103]
	v_pk_fma_f32 v[42:43], v[42:43], v[102:103], v[68:69] op_sel_hi:[1,0,1]
	v_sub_f32_e32 v46, v52, v54
	v_mul_f32_e32 v42, v45, v105
	v_pk_fma_f32 v[70:71], v[44:45], v[104:105], v[42:43] op_sel_hi:[1,1,0] neg_lo:[0,0,1] neg_hi:[0,0,1]
	v_mul_f32_e32 v42, v44, v105
	v_pk_fma_f32 v[72:73], v[44:45], v[104:105], v[42:43] op_sel:[1,0,0] op_sel_hi:[0,1,0]
	v_sub_f32_e32 v42, v48, v68
	v_mov_b32_e32 v48, v56
	v_mov_b32_e32 v49, v66
	v_mov_b32_e32 v44, v70
	v_mov_b32_e32 v45, v72
.LBB0_233:
	s_or_b64 exec, exec, s[44:45]
	v_cvt_pk_bf16_f32 v46, v46, v47
	v_cvt_pk_bf16_f32 v47, v48, v49
	v_cvt_pk_bf16_f32 v48, v42, v43
	v_cvt_pk_bf16_f32 v49, v44, v45
	global_store_dwordx4 v[50:51], v[46:49], off
	s_and_saveexec_b64 s[44:45], s[38:39]
	s_cbranch_execz .LBB0_235
	s_waitcnt vmcnt(3)
	s_nop 1
	v_pk_mul_f32 v[44:45], v[38:39], v[106:107] op_sel:[1,1] op_sel_hi:[0,1]
	v_pk_mul_f32 v[42:43], v[38:39], v[106:107]
	v_pk_fma_f32 v[38:39], v[38:39], v[106:107], v[44:45] op_sel_hi:[1,0,1]
	v_pk_mul_f32 v[52:53], v[34:35], v[102:103] op_sel:[1,1] op_sel_hi:[0,1]
	v_mul_f32_e32 v38, v41, v109
	v_pk_fma_f32 v[46:47], v[40:41], v[108:109], v[38:39] op_sel_hi:[1,1,0] neg_lo:[0,0,1] neg_hi:[0,0,1]
	v_mul_f32_e32 v38, v40, v109
	v_pk_fma_f32 v[48:49], v[40:41], v[108:109], v[38:39] op_sel:[1,0,0] op_sel_hi:[0,1,0]
	v_pk_mul_f32 v[40:41], v[34:35], v[102:103]
	v_pk_fma_f32 v[34:35], v[34:35], v[102:103], v[52:53] op_sel_hi:[1,0,1]
	v_sub_f32_e32 v38, v42, v44
	v_mul_f32_e32 v34, v37, v105
	v_pk_fma_f32 v[54:55], v[36:37], v[104:105], v[34:35] op_sel_hi:[1,1,0] neg_lo:[0,0,1] neg_hi:[0,0,1]
	v_mul_f32_e32 v34, v36, v105
	v_pk_fma_f32 v[56:57], v[36:37], v[104:105], v[34:35] op_sel:[1,0,0] op_sel_hi:[0,1,0]
	v_sub_f32_e32 v34, v40, v52
	v_mov_b32_e32 v40, v46
	v_mov_b32_e32 v41, v48
	v_mov_b32_e32 v36, v54
	v_mov_b32_e32 v37, v56

; __device__ __forceinline__ unsigned cvt_pk_bf16(float lo, float hi) { unsigned r; asm volatile("v_cvt_pk_bf16_f32 %0, %1, %2" : "=v"(r) : "v"(lo), "v"(hi)); return r; }
;     __device__ __forceinline__ void operator()(const f32x4 (&acc)[2][2][4][2], const Unit& u, int wr, int wc, int fr_, int fq_) const {
;     ...
;             for (int bj = 0; bj < 2; ++bj) {
;                 f32x4 v0 = acc[ai][bj][m][0], v1 = acc[ai][bj][m][1];
;                 if (rotl) {
;                     f32x4 w0, w1;
;                     w0[0] = v0[0] * cs0[0] - v0[1] * cs0[1]; w0[1] = v0[1] * cs0[0] + v0[0] * cs0[1];
;                     w0[2] = v0[2] * cs1[0] - v0[3] * cs1[1]; w0[3] = v0[3] * cs1[0] + v0[2] * cs1[1];
;                     w1[0] = v1[0] * cs2[0] - v1[1] * cs2[1]; w1[1] = v1[1] * cs2[0] + v1[0] * cs2[1];
;                     w1[2] = v1[2] * cs3[0] - v1[3] * cs3[1]; w1[3] = v1[3] * cs3[0] + v1[2] * cs3[1];
;                     v0 = w0; v1 = w1;
;                 }
;                 u32x4 w; w.x = cvt_pk_bf16(v0[0], v0[1]); w.y = cvt_pk_bf16(v0[2], v0[3]); w.z = cvt_pk_bf16(v1[0], v1[1]); w.w = cvt_pk_bf16(v1[2], v1[3]);
;                 *(u32x4*)(rowp + bj * hstep) = w;
.LBB0_240:
	s_waitcnt vmcnt(1)
	s_nop 1
	v_pk_mul_f32 v[38:39], v[30:31], v[82:83] op_sel:[1,1] op_sel_hi:[0,1]
	v_pk_mul_f32 v[36:37], v[30:31], v[82:83]
	v_pk_fma_f32 v[30:31], v[30:31], v[82:83], v[38:39] op_sel_hi:[1,0,1]
	v_pk_mul_f32 v[44:45], v[26:27], v[78:79] op_sel:[1,1] op_sel_hi:[0,1]
	v_mul_f32_e32 v30, v33, v85
	v_pk_fma_f32 v[40:41], v[32:33], v[84:85], v[30:31] op_sel_hi:[1,1,0] neg_lo:[0,0,1] neg_hi:[0,0,1]
	v_mul_f32_e32 v30, v32, v85
	v_pk_fma_f32 v[42:43], v[32:33], v[84:85], v[30:31] op_sel:[1,0,0] op_sel_hi:[0,1,0]
	v_pk_mul_f32 v[32:33], v[26:27], v[78:79]
	v_pk_fma_f32 v[26:27], v[26:27], v[78:79], v[44:45] op_sel_hi:[1,0,1]
	v_sub_f32_e32 v30, v36, v38
	v_mul_f32_e32 v26, v29, v81
	v_pk_fma_f32 v[46:47], v[28:29], v[80:81], v[26:27] op_sel_hi:[1,1,0] neg_lo:[0,0,1] neg_hi:[0,0,1]
	v_mul_f32_e32 v26, v28, v81
	v_pk_fma_f32 v[48:49], v[28:29], v[80:81], v[26:27] op_sel:[1,0,0] op_sel_hi:[0,1,0]
	v_sub_f32_e32 v26, v32, v44
	v_mov_b32_e32 v32, v40
	v_mov_b32_e32 v33, v42
	v_mov_b32_e32 v28, v46
	v_mov_b32_e32 v29, v48
.LBB0_241:
	s_or_b64 exec, exec, s[44:45]
	v_cvt_pk_bf16_f32 v30, v30, v31
	v_cvt_pk_bf16_f32 v31, v32, v33
	v_cvt_pk_bf16_f32 v32, v26, v27
	v_cvt_pk_bf16_f32 v33, v28, v29
	global_store_dwordx4 v[34:35], v[30:33], off
	s_and_saveexec_b64 s[44:45], s[38:39]
	s_cbranch_execz .LBB0_243
	s_waitcnt vmcnt(1)
	s_nop 1
	v_pk_mul_f32 v[28:29], v[22:23], v[82:83] op_sel:[1,1] op_sel_hi:[0,1]
	v_pk_mul_f32 v[26:27], v[22:23], v[82:83]
	v_pk_fma_f32 v[22:23], v[22:23], v[82:83], v[28:29] op_sel_hi:[1,0,1]
	v_pk_mul_f32 v[36:37], v[18:19], v[78:79] op_sel:[1,1] op_sel_hi:[0,1]
	v_mul_f32_e32 v22, v25, v85
	v_pk_fma_f32 v[30:31], v[24:25], v[84:85], v[22:23] op_sel_hi:[1,1,0] neg_lo:[0,0,1] neg_hi:[0,0,1]
	v_mul_f32_e32 v22, v24, v85
	v_pk_fma_f32 v[32:33], v[24:25], v[84:85], v[22:23] op_sel:[1,0,0] op_sel_hi:[0,1,0]
	v_pk_mul_f32 v[24:25], v[18:19], v[78:79]
	v_pk_fma_f32 v[18:19], v[18:19], v[78:79], v[36:37] op_sel_hi:[1,0,1]
	v_sub_f32_e32 v22, v26, v28
	v_mul_f32_e32 v18, v21, v81
	v_pk_fma_f32 v[38:39], v[20:21], v[80:81], v[18:19] op_sel_hi:[1,1,0] neg_lo:[0,0,1] neg_hi:[0,0,1]
	v_mul_f32_e32 v18, v20, v81
	v_pk_fma_f32 v[40:41], v[20:21], v[80:81], v[18:19] op_sel:[1,0,0] op_sel_hi:[0,1,0]
	v_sub_f32_e32 v18, v24, v36
	v_mov_b32_e32 v24, v30
	v_mov_b32_e32 v25, v32
	v_mov_b32_e32 v20, v38
	v_mov_b32_e32 v21, v40

; __device__ __forceinline__ unsigned cvt_pk_bf16(float lo, float hi) { unsigned r; asm volatile("v_cvt_pk_bf16_f32 %0, %1, %2" : "=v"(r) : "v"(lo), "v"(hi)); return r; }
;     __device__ __forceinline__ void operator()(const f32x4 (&acc)[2][2][4][2], const Unit& u, int wr, int wc, int fr_, int fq_) const {
;     ...
;             for (int bj = 0; bj < 2; ++bj) {
;                 f32x4 v0 = acc[ai][bj][m][0], v1 = acc[ai][bj][m][1];
;                 if (rotl) {
;                     f32x4 w0, w1;
;                     w0[0] = v0[0] * cs0[0] - v0[1] * cs0[1]; w0[1] = v0[1] * cs0[0] + v0[0] * cs0[1];
;                     w0[2] = v0[2] * cs1[0] - v0[3] * cs1[1]; w0[3] = v0[3] * cs1[0] + v0[2] * cs1[1];
;                     w1[0] = v1[0] * cs2[0] - v1[1] * cs2[1]; w1[1] = v1[1] * cs2[0] + v1[0] * cs2[1];
;                     w1[2] = v1[2] * cs3[0] - v1[3] * cs3[1]; w1[3] = v1[3] * cs3[0] + v1[2] * cs3[1];
;                     v0 = w0; v1 = w1;
;                 }
;                 u32x4 w; w.x = cvt_pk_bf16(v0[0], v0[1]); w.y = cvt_pk_bf16(v0[2], v0[3]); w.z = cvt_pk_bf16(v1[0], v1[1]); w.w = cvt_pk_bf16(v1[2], v1[3]);
;                 *(u32x4*)(rowp + bj * hstep) = w;
.LBB0_248:
	s_waitcnt vmcnt(0)
	s_nop 1
	v_pk_mul_f32 v[22:23], v[14:15], v[62:63] op_sel:[1,1] op_sel_hi:[0,1]
	v_pk_mul_f32 v[20:21], v[14:15], v[62:63]
	v_pk_fma_f32 v[14:15], v[14:15], v[62:63], v[22:23] op_sel_hi:[1,0,1]
	v_pk_mul_f32 v[28:29], v[10:11], v[58:59] op_sel:[1,1] op_sel_hi:[0,1]
	v_mul_f32_e32 v14, v17, v65
	v_pk_fma_f32 v[24:25], v[16:17], v[64:65], v[14:15] op_sel_hi:[1,1,0] neg_lo:[0,0,1] neg_hi:[0,0,1]
	v_mul_f32_e32 v14, v16, v65
	v_pk_fma_f32 v[26:27], v[16:17], v[64:65], v[14:15] op_sel:[1,0,0] op_sel_hi:[0,1,0]
	v_pk_mul_f32 v[16:17], v[10:11], v[58:59]
	v_pk_fma_f32 v[10:11], v[10:11], v[58:59], v[28:29] op_sel_hi:[1,0,1]
	v_sub_f32_e32 v14, v20, v22
	v_mul_f32_e32 v10, v13, v61
	v_pk_fma_f32 v[30:31], v[12:13], v[60:61], v[10:11] op_sel_hi:[1,1,0] neg_lo:[0,0,1] neg_hi:[0,0,1]
	v_mul_f32_e32 v10, v12, v61
	v_pk_fma_f32 v[32:33], v[12:13], v[60:61], v[10:11] op_sel:[1,0,0] op_sel_hi:[0,1,0]
	v_sub_f32_e32 v10, v16, v28
	v_mov_b32_e32 v16, v24
	v_mov_b32_e32 v17, v26
	v_mov_b32_e32 v12, v30
	v_mov_b32_e32 v13, v32
.LBB0_249:
	s_or_b64 exec, exec, s[40:41]
	v_cvt_pk_bf16_f32 v14, v14, v15
	v_cvt_pk_bf16_f32 v15, v16, v17
	v_cvt_pk_bf16_f32 v16, v10, v11
	v_cvt_pk_bf16_f32 v17, v12, v13
	global_store_dwordx4 v[18:19], v[14:17], off
	s_and_saveexec_b64 s[40:41], s[38:39]
	s_cbranch_execz .LBB0_251
	s_waitcnt vmcnt(0)
	s_nop 1
	v_pk_mul_f32 v[12:13], v[6:7], v[62:63] op_sel:[1,1] op_sel_hi:[0,1]
	v_pk_mul_f32 v[10:11], v[6:7], v[62:63]
	v_pk_fma_f32 v[6:7], v[6:7], v[62:63], v[12:13] op_sel_hi:[1,0,1]
	v_pk_mul_f32 v[20:21], v[2:3], v[58:59] op_sel:[1,1] op_sel_hi:[0,1]
	v_mul_f32_e32 v6, v9, v65
	v_pk_fma_f32 v[14:15], v[8:9], v[64:65], v[6:7] op_sel_hi:[1,1,0] neg_lo:[0,0,1] neg_hi:[0,0,1]
	v_mul_f32_e32 v6, v8, v65
	v_pk_fma_f32 v[16:17], v[8:9], v[64:65], v[6:7] op_sel:[1,0,0] op_sel_hi:[0,1,0]
	v_pk_mul_f32 v[8:9], v[2:3], v[58:59]
	v_pk_fma_f32 v[2:3], v[2:3], v[58:59], v[20:21] op_sel_hi:[1,0,1]
	v_sub_f32_e32 v6, v10, v12
	v_mul_f32_e32 v2, v5, v61
	v_pk_fma_f32 v[22:23], v[4:5], v[60:61], v[2:3] op_sel_hi:[1,1,0] neg_lo:[0,0,1] neg_hi:[0,0,1]
	v_mul_f32_e32 v2, v4, v61
	v_pk_fma_f32 v[24:25], v[4:5], v[60:61], v[2:3] op_sel:[1,0,0] op_sel_hi:[0,1,0]
	v_sub_f32_e32 v2, v8, v20
	v_mov_b32_e32 v8, v14
	v_mov_b32_e32 v9, v16
	v_mov_b32_e32 v4, v22
	v_mov_b32_e32 v5, v24
